# Q|K and V^T epilogue stores written through, no L2 writeback at the pre-attention pair barrier
# speedup vs baseline: 1.0025x; 1.0025x over previous
; __device__ __forceinline__ unsigned cvt_pk_bf16(float lo, float hi) { unsigned r; asm("v_cvt_pk_bf16_f32 %0, %1, %2" : "=v"(r) : "v"(lo), "v"(hi)); return r; }
; __device__ __forceinline__ float rms_r(ssq_t ssq) { float eps = RMS_EPS; asm volatile("" : "+v"(eps));
;     return 1.f / sqrtf(fmaf((float)ssq, 1.f / (SSQ_ONE * D), eps)); }
;     __device__ __forceinline__ void operator()(const Acc& acc, const Unit& u, int wr, int wc, int fr, int fq) const {
;     ...
;         for (int ai = 0; ai < 2; ++ai)
; #pragma unroll
;             for (int m = 0; m < 4; ++m) {
;                 const int row = row0 + ai * HALF + m * 16;
;                 const float rr = ssq ? rms_r(rrv[ai * 4 + m]) : 1.f;
;                 bf16_t* rowp = O + (size_t)row * ldc + col0;
; #pragma unroll
;                 for (int bj = 0; bj < 2; ++bj) {
;                     const f32x4 v0 = acc[ai][bj][m][0] * rr + bv[bj][0], v1 = acc[ai][bj][m][1] * rr + bv[bj][1];
;                     u32x4 w; w.x = cvt_pk_bf16(v0[0], v0[1]); w.y = cvt_pk_bf16(v0[2], v0[3]); w.z = cvt_pk_bf16(v1[0], v1[1]); w.w = cvt_pk_bf16(v1[2], v1[3]);
;                     *(u32x4*)(rowp + bj * HALF) = w;
.LBB0_333:
	v_lshlrev_b64 v[172:173], 13, v[156:157]
	v_lshl_add_u64 v[172:173], s[14:15], 0, v[172:173]
	v_lshl_add_u64 v[172:173], v[154:155], 1, v[172:173]
	v_pk_fma_f32 v[126:127], v[126:127], v[160:161], v[142:143] op_sel_hi:[1,0,1]
	v_pk_fma_f32 v[124:125], v[124:125], v[160:161], v[140:141] op_sel_hi:[1,0,1]
	v_pk_fma_f32 v[174:175], v[122:123], v[160:161], v[146:147] op_sel_hi:[1,0,1]
	v_pk_fma_f32 v[122:123], v[120:121], v[160:161], v[138:139] op_sel_hi:[1,0,1]
	v_cvt_pk_bf16_f32 v120, v124, v125
	v_cvt_pk_bf16_f32 v121, v126, v127
	s_and_b64 vcc, exec, s[2:3]
	v_cvt_pk_bf16_f32 v122, v122, v123
	v_cvt_pk_bf16_f32 v123, v174, v175
	global_store_dwordx4 v[172:173], v[120:123], off sc0 sc1
	v_pk_fma_f32 v[118:119], v[118:119], v[160:161], v[150:151] op_sel_hi:[1,0,1]
	v_pk_fma_f32 v[116:117], v[116:117], v[160:161], v[148:149] op_sel_hi:[1,0,1]
	v_pk_fma_f32 v[120:121], v[114:115], v[160:161], v[152:153] op_sel_hi:[1,0,1]
	v_pk_fma_f32 v[114:115], v[112:113], v[160:161], v[144:145] op_sel_hi:[1,0,1]
	v_cvt_pk_bf16_f32 v112, v116, v117
	v_cvt_pk_bf16_f32 v113, v118, v119
	s_nop 0
	v_cvt_pk_bf16_f32 v114, v114, v115
	v_cvt_pk_bf16_f32 v115, v120, v121
	global_store_dwordx4 v[172:173], v[112:115], off offset:256 sc0 sc1
	s_cbranch_vccnz .LBB0_335
	s_nop 0
	v_mov_b32_e32 v112, 0x358637bd
	s_nop 0
	v_fmac_f32_e32 v112, 0x36800000, v170
	v_mul_f32_e32 v113, 0x4f800000, v112
	v_cmp_gt_f32_e32 vcc, s66, v112
	s_nop 1
	v_cndmask_b32_e32 v112, v112, v113, vcc
	v_sqrt_f32_e32 v113, v112
	s_nop 0
	v_add_u32_e32 v114, -1, v113
	v_fma_f32 v116, -v114, v113, v112
	v_add_u32_e32 v115, 1, v113
	v_cmp_ge_f32_e64 s[4:5], 0, v116
	s_nop 1
	v_cndmask_b32_e64 v114, v113, v114, s[4:5]
	v_fma_f32 v113, -v115, v113, v112
	v_cmp_lt_f32_e64 s[4:5], 0, v113
	s_nop 1
	v_cndmask_b32_e64 v113, v114, v115, s[4:5]
	v_mul_f32_e32 v114, 0x37800000, v113
	v_cndmask_b32_e32 v113, v113, v114, vcc
	v_cmp_class_f32_e32 vcc, v112, v196
	s_nop 1
	v_cndmask_b32_e32 v112, v113, v112, vcc
	v_div_scale_f32 v113, s[0:1], v112, v112, 1.0
	v_rcp_f32_e32 v114, v113
	s_nop 0
	v_fma_f32 v115, -v113, v114, 1.0
	v_fmac_f32_e32 v114, v115, v114
	v_div_scale_f32 v115, vcc, 1.0, v112, 1.0
	v_mul_f32_e32 v116, v115, v114
	v_fma_f32 v117, -v113, v116, v115
	v_fmac_f32_e32 v116, v117, v114
	v_fma_f32 v113, -v113, v116, v115
	v_div_fmas_f32 v113, v113, v114, v116
	v_div_fixup_f32 v158, v113, v112, 1.0
.LBB0_335:
	s_nop 0
	v_or_b32_e32 v112, 16, v156
	v_ashrrev_i32_e32 v113, 31, v112
	v_lshlrev_b64 v[112:113], 13, v[112:113]
	v_lshl_add_u64 v[112:113], s[14:15], 0, v[112:113]
	v_lshl_add_u64 v[112:113], v[154:155], 1, v[112:113]
	v_pk_fma_f32 v[110:111], v[110:111], v[158:159], v[142:143] op_sel_hi:[1,0,1]
	v_pk_fma_f32 v[108:109], v[108:109], v[158:159], v[140:141] op_sel_hi:[1,0,1]
	v_pk_fma_f32 v[114:115], v[106:107], v[158:159], v[146:147] op_sel_hi:[1,0,1]
	v_pk_fma_f32 v[106:107], v[104:105], v[158:159], v[138:139] op_sel_hi:[1,0,1]
	v_cvt_pk_bf16_f32 v104, v108, v109
	v_cvt_pk_bf16_f32 v105, v110, v111
	v_pk_fma_f32 v[100:101], v[100:101], v[158:159], v[148:149] op_sel_hi:[1,0,1]
	v_cvt_pk_bf16_f32 v106, v106, v107
	v_cvt_pk_bf16_f32 v107, v114, v115
	global_store_dwordx4 v[112:113], v[104:107], off sc0 sc1
	v_pk_fma_f32 v[102:103], v[102:103], v[158:159], v[150:151] op_sel_hi:[1,0,1]
	s_and_b64 vcc, exec, s[2:3]
	v_pk_fma_f32 v[104:105], v[98:99], v[158:159], v[152:153] op_sel_hi:[1,0,1]
	v_pk_fma_f32 v[98:99], v[96:97], v[158:159], v[144:145] op_sel_hi:[1,0,1]
	v_cvt_pk_bf16_f32 v96, v100, v101
	v_cvt_pk_bf16_f32 v97, v102, v103
	s_nop 0
	v_cvt_pk_bf16_f32 v98, v98, v99
	v_cvt_pk_bf16_f32 v99, v104, v105
	global_store_dwordx4 v[112:113], v[96:99], off offset:256 sc0 sc1
	s_nop 1
	v_mov_b32_e32 v96, 1.0
	v_mov_b32_e32 v98, 1.0
	s_cbranch_vccnz .LBB0_337
	v_mov_b32_e32 v97, 0x358637bd
	s_nop 0
	v_fmac_f32_e32 v97, 0x36800000, v169
	v_mul_f32_e32 v98, 0x4f800000, v97
	v_cmp_gt_f32_e32 vcc, s66, v97
	s_nop 1
	v_cndmask_b32_e32 v97, v97, v98, vcc
	v_sqrt_f32_e32 v98, v97
	s_nop 0
	v_add_u32_e32 v99, -1, v98
	v_fma_f32 v101, -v99, v98, v97
	v_add_u32_e32 v100, 1, v98
	v_cmp_ge_f32_e64 s[4:5], 0, v101
	s_nop 1
	v_cndmask_b32_e64 v99, v98, v99, s[4:5]
	v_fma_f32 v98, -v100, v98, v97
	v_cmp_lt_f32_e64 s[4:5], 0, v98
	s_nop 1
	v_cndmask_b32_e64 v98, v99, v100, s[4:5]
	v_mul_f32_e32 v99, 0x37800000, v98
	v_cndmask_b32_e32 v98, v98, v99, vcc
	v_cmp_class_f32_e32 vcc, v97, v196
	s_nop 1
	v_cndmask_b32_e32 v97, v98, v97, vcc
	v_div_scale_f32 v98, s[0:1], v97, v97, 1.0
	v_rcp_f32_e32 v99, v98
	s_nop 0
	v_fma_f32 v100, -v98, v99, 1.0
	v_fmac_f32_e32 v99, v100, v99
	v_div_scale_f32 v100, vcc, 1.0, v97, 1.0
	v_mul_f32_e32 v101, v100, v99
	v_fma_f32 v102, -v98, v101, v100
	v_fmac_f32_e32 v101, v102, v99
	v_fma_f32 v98, -v98, v101, v100
	v_div_fmas_f32 v98, v98, v99, v101
	v_div_fixup_f32 v98, v98, v97, 1.0
; __device__ __forceinline__ unsigned cvt_pk_bf16(float lo, float hi) { unsigned r; asm("v_cvt_pk_bf16_f32 %0, %1, %2" : "=v"(r) : "v"(lo), "v"(hi)); return r; }
;     __device__ __forceinline__ void operator()(const Acc& acc, const Unit& u, int wr, int wc, int fr, int fq) const {
;     ...
;         for (int ai = 0; ai < 2; ++ai)
; #pragma unroll
;             for (int m = 0; m < 4; ++m) {
;                 const int row = row0 + ai * HALF + m * 16;
;                 const float rr = ssq ? rms_r(rrv[ai * 4 + m]) : 1.f;
;                 bf16_t* rowp = O + (size_t)row * ldc + col0;
; #pragma unroll
;                 for (int bj = 0; bj < 2; ++bj) {
;                     const f32x4 v0 = acc[ai][bj][m][0] * rr + bv[bj][0], v1 = acc[ai][bj][m][1] * rr + bv[bj][1];
;                     u32x4 w; w.x = cvt_pk_bf16(v0[0], v0[1]); w.y = cvt_pk_bf16(v0[2], v0[3]); w.z = cvt_pk_bf16(v1[0], v1[1]); w.w = cvt_pk_bf16(v1[2], v1[3]);
;                     *(u32x4*)(rowp + bj * HALF) = w;
.LBB0_337:
	v_or_b32_e32 v100, 32, v156
	v_ashrrev_i32_e32 v101, 31, v100
	v_lshlrev_b64 v[100:101], 13, v[100:101]
	v_lshl_add_u64 v[100:101], s[14:15], 0, v[100:101]
	v_lshl_add_u64 v[100:101], v[154:155], 1, v[100:101]
	v_pk_fma_f32 v[94:95], v[94:95], v[98:99], v[142:143] op_sel_hi:[1,0,1]
	v_pk_fma_f32 v[92:93], v[92:93], v[98:99], v[140:141] op_sel_hi:[1,0,1]
	v_pk_fma_f32 v[102:103], v[90:91], v[98:99], v[146:147] op_sel_hi:[1,0,1]
	v_pk_fma_f32 v[90:91], v[88:89], v[98:99], v[138:139] op_sel_hi:[1,0,1]
	v_cvt_pk_bf16_f32 v88, v92, v93
	v_cvt_pk_bf16_f32 v89, v94, v95
	s_and_b64 vcc, exec, s[2:3]
	v_cvt_pk_bf16_f32 v90, v90, v91
	v_cvt_pk_bf16_f32 v91, v102, v103
	global_store_dwordx4 v[100:101], v[88:91], off sc0 sc1
	v_pk_fma_f32 v[86:87], v[86:87], v[98:99], v[150:151] op_sel_hi:[1,0,1]
	v_pk_fma_f32 v[84:85], v[84:85], v[98:99], v[148:149] op_sel_hi:[1,0,1]
	v_pk_fma_f32 v[88:89], v[82:83], v[98:99], v[152:153] op_sel_hi:[1,0,1]
	v_pk_fma_f32 v[82:83], v[80:81], v[98:99], v[144:145] op_sel_hi:[1,0,1]
	v_cvt_pk_bf16_f32 v80, v84, v85
	v_cvt_pk_bf16_f32 v81, v86, v87
	s_nop 0
	v_cvt_pk_bf16_f32 v82, v82, v83
	v_cvt_pk_bf16_f32 v83, v88, v89
	global_store_dwordx4 v[100:101], v[80:83], off offset:256 sc0 sc1
	s_cbranch_vccnz .LBB0_339
	s_nop 0
	v_mov_b32_e32 v80, 0x358637bd
	s_nop 0
	v_fmac_f32_e32 v80, 0x36800000, v168
	v_mul_f32_e32 v81, 0x4f800000, v80
	v_cmp_gt_f32_e32 vcc, s66, v80
	s_nop 1
	v_cndmask_b32_e32 v80, v80, v81, vcc
	v_sqrt_f32_e32 v81, v80
	s_nop 0
	v_add_u32_e32 v82, -1, v81
	v_fma_f32 v84, -v82, v81, v80
	v_add_u32_e32 v83, 1, v81
	v_cmp_ge_f32_e64 s[4:5], 0, v84
	s_nop 1
	v_cndmask_b32_e64 v82, v81, v82, s[4:5]
	v_fma_f32 v81, -v83, v81, v80
	v_cmp_lt_f32_e64 s[4:5], 0, v81
	s_nop 1
	v_cndmask_b32_e64 v81, v82, v83, s[4:5]
	v_mul_f32_e32 v82, 0x37800000, v81
	v_cndmask_b32_e32 v81, v81, v82, vcc
	v_cmp_class_f32_e32 vcc, v80, v196
	s_nop 1
	v_cndmask_b32_e32 v80, v81, v80, vcc
	v_div_scale_f32 v81, s[0:1], v80, v80, 1.0
	v_rcp_f32_e32 v82, v81
	s_nop 0
	v_fma_f32 v83, -v81, v82, 1.0
	v_fmac_f32_e32 v82, v83, v82
	v_div_scale_f32 v83, vcc, 1.0, v80, 1.0
	v_mul_f32_e32 v84, v83, v82
	v_fma_f32 v85, -v81, v84, v83
	v_fmac_f32_e32 v84, v85, v82
	v_fma_f32 v81, -v81, v84, v83
	v_div_fmas_f32 v81, v81, v82, v84
	v_div_fixup_f32 v96, v81, v80, 1.0
.LBB0_339:
	s_nop 0
	v_or_b32_e32 v80, 48, v156
	v_ashrrev_i32_e32 v81, 31, v80
	v_lshlrev_b64 v[80:81], 13, v[80:81]
	v_lshl_add_u64 v[80:81], s[14:15], 0, v[80:81]
	v_lshl_add_u64 v[80:81], v[154:155], 1, v[80:81]
	v_pk_fma_f32 v[78:79], v[78:79], v[96:97], v[142:143] op_sel_hi:[1,0,1]
	v_pk_fma_f32 v[76:77], v[76:77], v[96:97], v[140:141] op_sel_hi:[1,0,1]
	v_pk_fma_f32 v[82:83], v[74:75], v[96:97], v[146:147] op_sel_hi:[1,0,1]
	v_pk_fma_f32 v[74:75], v[72:73], v[96:97], v[138:139] op_sel_hi:[1,0,1]
	v_cvt_pk_bf16_f32 v72, v76, v77
	v_cvt_pk_bf16_f32 v73, v78, v79
	v_pk_fma_f32 v[68:69], v[68:69], v[96:97], v[148:149] op_sel_hi:[1,0,1]
	v_cvt_pk_bf16_f32 v74, v74, v75
	v_cvt_pk_bf16_f32 v75, v82, v83
	global_store_dwordx4 v[80:81], v[72:75], off sc0 sc1
	v_pk_fma_f32 v[70:71], v[70:71], v[96:97], v[150:151] op_sel_hi:[1,0,1]
	s_and_b64 vcc, exec, s[2:3]
	v_pk_fma_f32 v[72:73], v[66:67], v[96:97], v[152:153] op_sel_hi:[1,0,1]
	v_pk_fma_f32 v[66:67], v[64:65], v[96:97], v[144:145] op_sel_hi:[1,0,1]
	v_cvt_pk_bf16_f32 v64, v68, v69
	v_cvt_pk_bf16_f32 v65, v70, v71
	v_mov_b32_e32 v68, 1.0
	v_cvt_pk_bf16_f32 v66, v66, v67
	v_cvt_pk_bf16_f32 v67, v72, v73
	global_store_dwordx4 v[80:81], v[64:67], off offset:256 sc0 sc1
	s_nop 1
	v_mov_b32_e32 v64, 1.0
	s_cbranch_vccnz .LBB0_341
	v_mov_b32_e32 v65, 0x358637bd
	s_nop 0
	v_fmac_f32_e32 v65, 0x36800000, v167
	v_mul_f32_e32 v66, 0x4f800000, v65
	v_cmp_gt_f32_e32 vcc, s66, v65
	s_nop 1
	v_cndmask_b32_e32 v65, v65, v66, vcc
	v_sqrt_f32_e32 v66, v65
	s_nop 0
	v_add_u32_e32 v67, -1, v66
	v_fma_f32 v69, -v67, v66, v65
	v_add_u32_e32 v68, 1, v66
	v_cmp_ge_f32_e64 s[4:5], 0, v69
	s_nop 1
	v_cndmask_b32_e64 v67, v66, v67, s[4:5]
	v_fma_f32 v66, -v68, v66, v65
	v_cmp_lt_f32_e64 s[4:5], 0, v66
	s_nop 1
	v_cndmask_b32_e64 v66, v67, v68, s[4:5]
	v_mul_f32_e32 v67, 0x37800000, v66
	v_cndmask_b32_e32 v66, v66, v67, vcc
	v_cmp_class_f32_e32 vcc, v65, v196
	s_nop 1
	v_cndmask_b32_e32 v65, v66, v65, vcc
	v_div_scale_f32 v66, s[0:1], v65, v65, 1.0
	v_rcp_f32_e32 v67, v66
	s_nop 0
	v_fma_f32 v68, -v66, v67, 1.0
	v_fmac_f32_e32 v67, v68, v67
	v_div_scale_f32 v68, vcc, 1.0, v65, 1.0
	v_mul_f32_e32 v69, v68, v67
	v_fma_f32 v70, -v66, v69, v68
	v_fmac_f32_e32 v69, v70, v67
	v_fma_f32 v66, -v66, v69, v68
	v_div_fmas_f32 v66, v66, v67, v69
	v_div_fixup_f32 v68, v66, v65, 1.0
; __device__ __forceinline__ unsigned cvt_pk_bf16(float lo, float hi) { unsigned r; asm("v_cvt_pk_bf16_f32 %0, %1, %2" : "=v"(r) : "v"(lo), "v"(hi)); return r; }
;     __device__ __forceinline__ void operator()(const Acc& acc, const Unit& u, int wr, int wc, int fr, int fq) const {
;     ...
;         for (int ai = 0; ai < 2; ++ai)
; #pragma unroll
;             for (int m = 0; m < 4; ++m) {
;                 const int row = row0 + ai * HALF + m * 16;
;                 const float rr = ssq ? rms_r(rrv[ai * 4 + m]) : 1.f;
;                 bf16_t* rowp = O + (size_t)row * ldc + col0;
; #pragma unroll
;                 for (int bj = 0; bj < 2; ++bj) {
;                     const f32x4 v0 = acc[ai][bj][m][0] * rr + bv[bj][0], v1 = acc[ai][bj][m][1] * rr + bv[bj][1];
;                     u32x4 w; w.x = cvt_pk_bf16(v0[0], v0[1]); w.y = cvt_pk_bf16(v0[2], v0[3]); w.z = cvt_pk_bf16(v1[0], v1[1]); w.w = cvt_pk_bf16(v1[2], v1[3]);
;                     *(u32x4*)(rowp + bj * HALF) = w;
.LBB0_341:
	v_lshlrev_b64 v[66:67], 13, v[156:157]
	v_lshl_add_u64 v[66:67], s[14:15], 0, v[66:67]
	v_lshl_add_u64 v[66:67], v[154:155], 1, v[66:67]
	s_mov_b64 s[0:1], 0x100000
	v_lshl_add_u64 v[70:71], v[66:67], 0, s[0:1]
	v_pk_fma_f32 v[60:61], v[60:61], v[68:69], v[140:141] op_sel_hi:[1,0,1]
	s_mov_b32 s0, 0x100000
	v_pk_fma_f32 v[72:73], v[58:59], v[68:69], v[146:147] op_sel_hi:[1,0,1]
	v_pk_fma_f32 v[58:59], v[56:57], v[68:69], v[138:139] op_sel_hi:[1,0,1]
	v_cvt_pk_bf16_f32 v56, v60, v61
	v_add_co_u32_e32 v60, vcc, s0, v66
	v_pk_fma_f32 v[62:63], v[62:63], v[68:69], v[142:143] op_sel_hi:[1,0,1]
	s_nop 0
	v_addc_co_u32_e32 v61, vcc, 0, v67, vcc
	v_cvt_pk_bf16_f32 v57, v62, v63
	v_cvt_pk_bf16_f32 v58, v58, v59
	v_cvt_pk_bf16_f32 v59, v72, v73
	global_store_dwordx4 v[60:61], v[56:59], off sc0 sc1
	s_and_b64 vcc, exec, s[2:3]
	v_pk_fma_f32 v[54:55], v[54:55], v[68:69], v[150:151] op_sel_hi:[1,0,1]
	v_pk_fma_f32 v[56:57], v[50:51], v[68:69], v[152:153] op_sel_hi:[1,0,1]
	v_pk_fma_f32 v[50:51], v[48:49], v[68:69], v[144:145] op_sel_hi:[1,0,1]
	v_pk_fma_f32 v[52:53], v[52:53], v[68:69], v[148:149] op_sel_hi:[1,0,1]
	v_cvt_pk_bf16_f32 v49, v54, v55
	v_cvt_pk_bf16_f32 v50, v50, v51
	v_cvt_pk_bf16_f32 v51, v56, v57
	s_nop 0
	v_cvt_pk_bf16_f32 v48, v52, v53
	global_store_dwordx4 v[70:71], v[48:51], off offset:256 sc0 sc1
	s_cbranch_vccnz .LBB0_343
	s_nop 0
	v_mov_b32_e32 v48, 0x358637bd
	s_nop 0
	v_fmac_f32_e32 v48, 0x36800000, v166
	v_mul_f32_e32 v49, 0x4f800000, v48
	v_cmp_gt_f32_e32 vcc, s66, v48
	s_nop 1
	v_cndmask_b32_e32 v48, v48, v49, vcc
	v_sqrt_f32_e32 v49, v48
	s_nop 0
	v_add_u32_e32 v50, -1, v49
	v_fma_f32 v52, -v50, v49, v48
	v_add_u32_e32 v51, 1, v49
	v_cmp_ge_f32_e64 s[4:5], 0, v52
	s_nop 1
	v_cndmask_b32_e64 v50, v49, v50, s[4:5]
	v_fma_f32 v49, -v51, v49, v48
	v_cmp_lt_f32_e64 s[4:5], 0, v49
	s_nop 1
	v_cndmask_b32_e64 v49, v50, v51, s[4:5]
	v_mul_f32_e32 v50, 0x37800000, v49
	v_cndmask_b32_e32 v49, v49, v50, vcc
	v_cmp_class_f32_e32 vcc, v48, v196
	s_nop 1
	v_cndmask_b32_e32 v48, v49, v48, vcc
	v_div_scale_f32 v49, s[0:1], v48, v48, 1.0
	v_rcp_f32_e32 v50, v49
	s_nop 0
	v_fma_f32 v51, -v49, v50, 1.0
	v_fmac_f32_e32 v50, v51, v50
	v_div_scale_f32 v51, vcc, 1.0, v48, 1.0
	v_mul_f32_e32 v52, v51, v50
	v_fma_f32 v53, -v49, v52, v51
	v_fmac_f32_e32 v52, v53, v50
	v_fma_f32 v49, -v49, v52, v51
	v_div_fmas_f32 v49, v49, v50, v52
	v_div_fixup_f32 v64, v49, v48, 1.0
.LBB0_343:
	s_mov_b64 s[0:1], 0x120000
	v_lshl_add_u64 v[48:49], v[66:67], 0, s[0:1]
	v_pk_fma_f32 v[44:45], v[44:45], v[64:65], v[140:141] op_sel_hi:[1,0,1]
	s_mov_b32 s0, 0x120000
	v_pk_fma_f32 v[50:51], v[42:43], v[64:65], v[146:147] op_sel_hi:[1,0,1]
	v_pk_fma_f32 v[42:43], v[40:41], v[64:65], v[138:139] op_sel_hi:[1,0,1]
	v_cvt_pk_bf16_f32 v40, v44, v45
	v_add_co_u32_e32 v44, vcc, s0, v66
	v_pk_fma_f32 v[46:47], v[46:47], v[64:65], v[142:143] op_sel_hi:[1,0,1]
	s_nop 0
	v_addc_co_u32_e32 v45, vcc, 0, v67, vcc
	v_cvt_pk_bf16_f32 v41, v46, v47
	v_cvt_pk_bf16_f32 v42, v42, v43
	v_cvt_pk_bf16_f32 v43, v50, v51
	global_store_dwordx4 v[44:45], v[40:43], off sc0 sc1
	v_pk_fma_f32 v[36:37], v[36:37], v[64:65], v[148:149] op_sel_hi:[1,0,1]
	v_pk_fma_f32 v[38:39], v[38:39], v[64:65], v[150:151] op_sel_hi:[1,0,1]
	v_pk_fma_f32 v[40:41], v[34:35], v[64:65], v[152:153] op_sel_hi:[1,0,1]
	v_pk_fma_f32 v[34:35], v[32:33], v[64:65], v[144:145] op_sel_hi:[1,0,1]
	v_cvt_pk_bf16_f32 v32, v36, v37
	v_cvt_pk_bf16_f32 v33, v38, v39
	s_and_b64 vcc, exec, s[2:3]
	v_cvt_pk_bf16_f32 v34, v34, v35
	v_cvt_pk_bf16_f32 v35, v40, v41
	global_store_dwordx4 v[48:49], v[32:35], off offset:256 sc0 sc1
	v_mov_b32_e32 v36, 1.0
	s_nop 0
	v_mov_b32_e32 v32, 1.0
	s_cbranch_vccnz .LBB0_345
	v_mov_b32_e32 v33, 0x358637bd
	s_nop 0
	v_fmac_f32_e32 v33, 0x36800000, v165
	v_mul_f32_e32 v34, 0x4f800000, v33
	v_cmp_gt_f32_e32 vcc, s66, v33
	s_nop 1
	v_cndmask_b32_e32 v33, v33, v34, vcc
	v_sqrt_f32_e32 v34, v33
	s_nop 0
	v_add_u32_e32 v35, -1, v34
	v_fma_f32 v37, -v35, v34, v33
	v_add_u32_e32 v36, 1, v34
	v_cmp_ge_f32_e64 s[4:5], 0, v37
	s_nop 1
	v_cndmask_b32_e64 v35, v34, v35, s[4:5]
	v_fma_f32 v34, -v36, v34, v33
	v_cmp_lt_f32_e64 s[4:5], 0, v34
	s_nop 1
	v_cndmask_b32_e64 v34, v35, v36, s[4:5]
	v_mul_f32_e32 v35, 0x37800000, v34
	v_cndmask_b32_e32 v34, v34, v35, vcc
	v_cmp_class_f32_e32 vcc, v33, v196
	s_nop 1
	v_cndmask_b32_e32 v33, v34, v33, vcc
	v_div_scale_f32 v34, s[0:1], v33, v33, 1.0
	v_rcp_f32_e32 v35, v34
	s_nop 0
	v_fma_f32 v36, -v34, v35, 1.0
	v_fmac_f32_e32 v35, v36, v35
	v_div_scale_f32 v36, vcc, 1.0, v33, 1.0
	v_mul_f32_e32 v37, v36, v35
	v_fma_f32 v38, -v34, v37, v36
	v_fmac_f32_e32 v37, v38, v35
	v_fma_f32 v34, -v34, v37, v36
	v_div_fmas_f32 v34, v34, v35, v37
	v_div_fixup_f32 v36, v34, v33, 1.0
; __device__ __forceinline__ unsigned cvt_pk_bf16(float lo, float hi) { unsigned r; asm("v_cvt_pk_bf16_f32 %0, %1, %2" : "=v"(r) : "v"(lo), "v"(hi)); return r; }
;     __device__ __forceinline__ void operator()(const Acc& acc, const Unit& u, int wr, int wc, int fr, int fq) const {
;     ...
;         for (int ai = 0; ai < 2; ++ai)
; #pragma unroll
;             for (int m = 0; m < 4; ++m) {
;                 const int row = row0 + ai * HALF + m * 16;
;                 const float rr = ssq ? rms_r(rrv[ai * 4 + m]) : 1.f;
;                 bf16_t* rowp = O + (size_t)row * ldc + col0;
; #pragma unroll
;                 for (int bj = 0; bj < 2; ++bj) {
;                     const f32x4 v0 = acc[ai][bj][m][0] * rr + bv[bj][0], v1 = acc[ai][bj][m][1] * rr + bv[bj][1];
;                     u32x4 w; w.x = cvt_pk_bf16(v0[0], v0[1]); w.y = cvt_pk_bf16(v0[2], v0[3]); w.z = cvt_pk_bf16(v1[0], v1[1]); w.w = cvt_pk_bf16(v1[2], v1[3]);
;                     *(u32x4*)(rowp + bj * HALF) = w;
.LBB0_345:
	v_lshlrev_b64 v[34:35], 13, v[156:157]
	v_lshl_add_u64 v[34:35], s[14:15], 0, v[34:35]
	v_lshl_add_u64 v[34:35], v[154:155], 1, v[34:35]
	s_mov_b64 s[0:1], 0x140000
	v_lshl_add_u64 v[38:39], v[34:35], 0, s[0:1]
	v_pk_fma_f32 v[28:29], v[28:29], v[36:37], v[140:141] op_sel_hi:[1,0,1]
	s_mov_b32 s0, 0x140000
	v_pk_fma_f32 v[40:41], v[26:27], v[36:37], v[146:147] op_sel_hi:[1,0,1]
	v_pk_fma_f32 v[26:27], v[24:25], v[36:37], v[138:139] op_sel_hi:[1,0,1]
	v_cvt_pk_bf16_f32 v24, v28, v29
	v_add_co_u32_e32 v28, vcc, s0, v34
	v_pk_fma_f32 v[30:31], v[30:31], v[36:37], v[142:143] op_sel_hi:[1,0,1]
	s_nop 0
	v_addc_co_u32_e32 v29, vcc, 0, v35, vcc
	v_cvt_pk_bf16_f32 v25, v30, v31
	v_cvt_pk_bf16_f32 v26, v26, v27
	v_cvt_pk_bf16_f32 v27, v40, v41
	global_store_dwordx4 v[28:29], v[24:27], off sc0 sc1
	s_and_b64 vcc, exec, s[2:3]
	v_pk_fma_f32 v[22:23], v[22:23], v[36:37], v[150:151] op_sel_hi:[1,0,1]
	v_pk_fma_f32 v[24:25], v[18:19], v[36:37], v[152:153] op_sel_hi:[1,0,1]
	v_pk_fma_f32 v[18:19], v[16:17], v[36:37], v[144:145] op_sel_hi:[1,0,1]
	v_pk_fma_f32 v[20:21], v[20:21], v[36:37], v[148:149] op_sel_hi:[1,0,1]
	v_cvt_pk_bf16_f32 v17, v22, v23
	v_cvt_pk_bf16_f32 v18, v18, v19
	v_cvt_pk_bf16_f32 v19, v24, v25
	s_nop 0
	v_cvt_pk_bf16_f32 v16, v20, v21
	global_store_dwordx4 v[38:39], v[16:19], off offset:256 sc0 sc1
	s_cbranch_vccnz .LBB0_347
	s_nop 0
	v_mov_b32_e32 v16, 0x358637bd
	s_nop 0
	v_fmac_f32_e32 v16, 0x36800000, v159
	v_mul_f32_e32 v17, 0x4f800000, v16
	v_cmp_gt_f32_e32 vcc, s66, v16
	s_nop 1
	v_cndmask_b32_e32 v16, v16, v17, vcc
	v_sqrt_f32_e32 v17, v16
	s_nop 0
	v_add_u32_e32 v18, -1, v17
	v_fma_f32 v20, -v18, v17, v16
	v_add_u32_e32 v19, 1, v17
	v_cmp_ge_f32_e64 s[2:3], 0, v20
	s_nop 1
	v_cndmask_b32_e64 v18, v17, v18, s[2:3]
	v_fma_f32 v17, -v19, v17, v16
	v_cmp_lt_f32_e64 s[2:3], 0, v17
	s_nop 1
	v_cndmask_b32_e64 v17, v18, v19, s[2:3]
	v_mul_f32_e32 v18, 0x37800000, v17
	v_cndmask_b32_e32 v17, v17, v18, vcc
	v_cmp_class_f32_e32 vcc, v16, v196
	s_nop 1
	v_cndmask_b32_e32 v16, v17, v16, vcc
	v_div_scale_f32 v17, s[0:1], v16, v16, 1.0
	v_rcp_f32_e32 v18, v17
	s_nop 0
	v_fma_f32 v19, -v17, v18, 1.0
	v_fmac_f32_e32 v18, v19, v18
	v_div_scale_f32 v19, vcc, 1.0, v16, 1.0
	v_mul_f32_e32 v20, v19, v18
	v_fma_f32 v21, -v17, v20, v19
	v_fmac_f32_e32 v20, v21, v18
	v_fma_f32 v17, -v17, v20, v19
	v_div_fmas_f32 v17, v17, v18, v20
	v_div_fixup_f32 v32, v17, v16, 1.0
.LBB0_347:
	s_mov_b64 s[0:1], 0x160000
	v_lshl_add_u64 v[16:17], v[34:35], 0, s[0:1]
	v_pk_fma_f32 v[12:13], v[12:13], v[32:33], v[140:141] op_sel_hi:[1,0,1]
	s_mov_b32 s0, 0x160000
	v_pk_fma_f32 v[18:19], v[10:11], v[32:33], v[146:147] op_sel_hi:[1,0,1]
	v_pk_fma_f32 v[10:11], v[8:9], v[32:33], v[138:139] op_sel_hi:[1,0,1]
	v_cvt_pk_bf16_f32 v8, v12, v13
	v_add_co_u32_e32 v12, vcc, s0, v34
	v_pk_fma_f32 v[14:15], v[14:15], v[32:33], v[142:143] op_sel_hi:[1,0,1]
	s_nop 0
	v_addc_co_u32_e32 v13, vcc, 0, v35, vcc
	v_cvt_pk_bf16_f32 v9, v14, v15
	v_cvt_pk_bf16_f32 v10, v10, v11
	v_cvt_pk_bf16_f32 v11, v18, v19
	global_store_dwordx4 v[12:13], v[8:11], off sc0 sc1
	s_andn2_b64 vcc, exec, s[36:37]
	s_mov_b64 s[0:1], -1
	v_pk_fma_f32 v[8:9], v[2:3], v[32:33], v[152:153] op_sel_hi:[1,0,1]
	v_pk_fma_f32 v[2:3], v[0:1], v[32:33], v[144:145] op_sel_hi:[1,0,1]
	v_pk_fma_f32 v[6:7], v[6:7], v[32:33], v[150:151] op_sel_hi:[1,0,1]
	v_pk_fma_f32 v[4:5], v[4:5], v[32:33], v[148:149] op_sel_hi:[1,0,1]
	v_cvt_pk_bf16_f32 v1, v6, v7
	v_cvt_pk_bf16_f32 v2, v2, v3
	v_cvt_pk_bf16_f32 v3, v8, v9
	s_nop 0
	v_cvt_pk_bf16_f32 v0, v4, v5
	global_store_dwordx4 v[16:17], v[0:3], off offset:256 sc0 sc1
	s_cbranch_vccnz .LBB0_302
	s_andn2_b64 vcc, exec, s[6:7]
	s_cbranch_vccnz .LBB0_301
	s_barrier
	s_branch .LBB0_301

; __device__ __forceinline__ float rms_r(ssq_t ssq) { float eps = RMS_EPS; asm volatile("" : "+v"(eps));
;     return 1.f / sqrtf(fmaf((float)ssq, 1.f / (SSQ_ONE * D), eps)); }
;     __device__ __forceinline__ void operator()(const Acc& acc, const Unit& u, int wr, int wc, int fr, int fq) const {
;         const int row0 = u.pm * BM + wr * 64 + fr, col0 = u.pn * BM + wc * 32 + 8 * fq;
;         f32x4 rv[2][2];
; #pragma unroll
;         for (int bj = 0; bj < 2; ++bj)
; #pragma unroll
;             for (int n = 0; n < 2; ++n) { const ssq_t* s = ssq + col0 + bj * HALF + 4 * n; rv[bj][n] = (f32x4){rms_r(s[0]), rms_r(s[1]), rms_r(s[2]), rms_r(s[3])}; }
.LBB0_361:
	v_lshl_or_b32 v142, s1, 8, v165
	v_ashrrev_i32_e32 v143, 31, v142
	v_lshl_add_u64 v[146:147], v[142:143], 2, s[14:15]
	global_load_dword v138, v[146:147], off
	v_mov_b32_e32 v139, 0x358637bd
	v_lshlrev_b64 v[178:179], 1, v[142:143]
	s_mov_b32 s69, 0x14000
	s_mov_b32 s35, 0x30000
	s_mov_b32 s68, 0xb0000
	s_mov_b32 s34, 0x40000
	s_mov_b32 s58, 0x34000
	s_mov_b32 s59, 0x38000
	s_mov_b32 s60, 0x3c000
	s_mov_b32 s61, 0x44000
	s_mov_b32 s62, 0x48000
	s_mov_b32 s63, 0x4c000
	s_waitcnt vmcnt(0)
	v_cvt_f32_u32_e32 v138, v138
	v_fmac_f32_e32 v139, 0x36800000, v138
	v_cmp_gt_f32_e32 vcc, s66, v139
	v_mul_f32_e32 v138, 0x4f800000, v139
	s_nop 0
	v_cndmask_b32_e32 v138, v139, v138, vcc
	v_sqrt_f32_e32 v139, v138
	s_nop 0
	v_add_u32_e32 v140, -1, v139
	v_fma_f32 v141, -v140, v139, v138
	v_cmp_ge_f32_e64 s[2:3], 0, v141
	v_add_u32_e32 v141, 1, v139
	s_nop 0
	v_cndmask_b32_e64 v140, v139, v140, s[2:3]
	v_fma_f32 v139, -v141, v139, v138
	v_cmp_lt_f32_e64 s[2:3], 0, v139
	s_nop 1
	v_cndmask_b32_e64 v139, v140, v141, s[2:3]
	v_mul_f32_e32 v140, 0x37800000, v139
	v_cndmask_b32_e32 v139, v139, v140, vcc
	v_cmp_class_f32_e32 vcc, v138, v196
	s_nop 1
	v_cndmask_b32_e32 v138, v139, v138, vcc
	v_div_scale_f32 v139, s[2:3], v138, v138, 1.0
	v_rcp_f32_e32 v140, v139
	s_nop 0
	v_fma_f32 v141, -v139, v140, 1.0
	v_fmac_f32_e32 v140, v141, v140
	v_div_scale_f32 v141, vcc, 1.0, v138, 1.0
	v_mul_f32_e32 v144, v141, v140
	v_fma_f32 v145, -v139, v144, v141
	v_fmac_f32_e32 v144, v145, v140
	v_fma_f32 v139, -v139, v144, v141
	v_div_fmas_f32 v139, v139, v140, v144
	v_div_fixup_f32 v138, v139, v138, 1.0
	global_load_dword v139, v[146:147], off offset:4
	v_mov_b32_e32 v140, 0x358637bd
	s_waitcnt vmcnt(0)
	v_cvt_f32_u32_e32 v139, v139
	v_fmac_f32_e32 v140, 0x36800000, v139
	v_cmp_gt_f32_e32 vcc, s66, v140
	v_mul_f32_e32 v139, 0x4f800000, v140
	s_nop 0
	v_cndmask_b32_e32 v139, v140, v139, vcc
	v_sqrt_f32_e32 v140, v139
	s_nop 0
	v_add_u32_e32 v141, -1, v140
	v_fma_f32 v144, -v141, v140, v139
	v_cmp_ge_f32_e64 s[2:3], 0, v144
	v_add_u32_e32 v144, 1, v140
	s_nop 0
	v_cndmask_b32_e64 v141, v140, v141, s[2:3]
	v_fma_f32 v140, -v144, v140, v139
	v_cmp_lt_f32_e64 s[2:3], 0, v140
	s_nop 1
	v_cndmask_b32_e64 v140, v141, v144, s[2:3]
	v_mul_f32_e32 v141, 0x37800000, v140
	v_cndmask_b32_e32 v140, v140, v141, vcc
	v_cmp_class_f32_e32 vcc, v139, v196
	s_nop 1
	v_cndmask_b32_e32 v139, v140, v139, vcc
	v_div_scale_f32 v140, s[2:3], v139, v139, 1.0
	v_rcp_f32_e32 v141, v140
	s_nop 0
	v_fma_f32 v144, -v140, v141, 1.0
	v_fmac_f32_e32 v141, v144, v141
	v_div_scale_f32 v144, vcc, 1.0, v139, 1.0
	v_mul_f32_e32 v145, v144, v141
	v_fma_f32 v148, -v140, v145, v144
	v_fmac_f32_e32 v145, v148, v141
	v_fma_f32 v140, -v140, v145, v144
	v_div_fmas_f32 v140, v140, v141, v145
	v_div_fixup_f32 v139, v140, v139, 1.0
	global_load_dword v140, v[146:147], off offset:8
	v_mov_b32_e32 v141, 0x358637bd
	s_waitcnt vmcnt(0)
	v_cvt_f32_u32_e32 v140, v140
	v_fmac_f32_e32 v141, 0x36800000, v140
	v_cmp_gt_f32_e32 vcc, s66, v141
	v_mul_f32_e32 v140, 0x4f800000, v141
	s_nop 0
	v_cndmask_b32_e32 v140, v141, v140, vcc
	v_sqrt_f32_e32 v141, v140
	s_nop 0
	v_add_u32_e32 v144, -1, v141
	v_fma_f32 v145, -v144, v141, v140
	v_cmp_ge_f32_e64 s[2:3], 0, v145
	v_add_u32_e32 v145, 1, v141
	s_nop 0
	v_cndmask_b32_e64 v144, v141, v144, s[2:3]
	v_fma_f32 v141, -v145, v141, v140
	v_cmp_lt_f32_e64 s[2:3], 0, v141
	s_nop 1
	v_cndmask_b32_e64 v141, v144, v145, s[2:3]
	v_mul_f32_e32 v144, 0x37800000, v141
	v_cndmask_b32_e32 v141, v141, v144, vcc
	v_cmp_class_f32_e32 vcc, v140, v196
	s_nop 1
	v_cndmask_b32_e32 v140, v141, v140, vcc
	v_div_scale_f32 v141, s[2:3], v140, v140, 1.0
	v_rcp_f32_e32 v144, v141
	s_nop 0
	v_fma_f32 v145, -v141, v144, 1.0
	v_fmac_f32_e32 v144, v145, v144
	v_div_scale_f32 v145, vcc, 1.0, v140, 1.0
	v_mul_f32_e32 v148, v145, v144
	v_fma_f32 v149, -v141, v148, v145
	v_fmac_f32_e32 v148, v149, v144
	v_fma_f32 v141, -v141, v148, v145
	v_div_fmas_f32 v141, v141, v144, v148
	v_div_fixup_f32 v140, v141, v140, 1.0
	global_load_dword v141, v[146:147], off offset:12
	v_mov_b32_e32 v144, 0x358637bd
	s_waitcnt vmcnt(0)
	v_cvt_f32_u32_e32 v141, v141
	v_fmac_f32_e32 v144, 0x36800000, v141
	v_cmp_gt_f32_e32 vcc, s66, v144
	v_mul_f32_e32 v141, 0x4f800000, v144
	s_nop 0
	v_cndmask_b32_e32 v141, v144, v141, vcc
	v_sqrt_f32_e32 v144, v141
	s_nop 0
	v_add_u32_e32 v145, -1, v144
	v_fma_f32 v148, -v145, v144, v141
	v_cmp_ge_f32_e64 s[2:3], 0, v148
	v_add_u32_e32 v148, 1, v144
	s_nop 0
	v_cndmask_b32_e64 v145, v144, v145, s[2:3]
	v_fma_f32 v144, -v148, v144, v141
	v_cmp_lt_f32_e64 s[2:3], 0, v144
	s_nop 1
	v_cndmask_b32_e64 v144, v145, v148, s[2:3]
	v_mul_f32_e32 v145, 0x37800000, v144
	v_cndmask_b32_e32 v144, v144, v145, vcc
	v_cmp_class_f32_e32 vcc, v141, v196
	s_nop 1
	v_cndmask_b32_e32 v141, v144, v141, vcc
	v_div_scale_f32 v144, s[2:3], v141, v141, 1.0
	v_rcp_f32_e32 v145, v144
	s_nop 0
	v_fma_f32 v148, -v144, v145, 1.0
	v_fmac_f32_e32 v145, v148, v145
	v_div_scale_f32 v148, vcc, 1.0, v141, 1.0
	v_mul_f32_e32 v149, v148, v145
	v_fma_f32 v150, -v144, v149, v148
	v_fmac_f32_e32 v149, v150, v145
	v_fma_f32 v144, -v144, v149, v148
	v_div_fmas_f32 v144, v144, v145, v149
	v_div_fixup_f32 v141, v144, v141, 1.0
	global_load_dword v144, v[146:147], off offset:16
	v_mov_b32_e32 v145, 0x358637bd
	s_waitcnt vmcnt(0)
; __device__ __forceinline__ float rms_r(ssq_t ssq) { float eps = RMS_EPS; asm volatile("" : "+v"(eps));
;     return 1.f / sqrtf(fmaf((float)ssq, 1.f / (SSQ_ONE * D), eps)); }
;     __device__ __forceinline__ void operator()(const Acc& acc, const Unit& u, int wr, int wc, int fr, int fq) const {
;     ...
;         for (int bj = 0; bj < 2; ++bj)
; #pragma unroll
;             for (int n = 0; n < 2; ++n) { const ssq_t* s = ssq + col0 + bj * HALF + 4 * n; rv[bj][n] = (f32x4){rms_r(s[0]), rms_r(s[1]), rms_r(s[2]), rms_r(s[3])}; }
	v_cvt_f32_u32_e32 v144, v144
	v_fmac_f32_e32 v145, 0x36800000, v144
	v_cmp_gt_f32_e32 vcc, s66, v145
	v_mul_f32_e32 v144, 0x4f800000, v145
	s_nop 0
	v_cndmask_b32_e32 v144, v145, v144, vcc
	v_sqrt_f32_e32 v145, v144
	s_nop 0
	v_add_u32_e32 v148, -1, v145
	v_fma_f32 v149, -v148, v145, v144
	v_cmp_ge_f32_e64 s[2:3], 0, v149
	v_add_u32_e32 v149, 1, v145
	s_nop 0
	v_cndmask_b32_e64 v148, v145, v148, s[2:3]
	v_fma_f32 v145, -v149, v145, v144
	v_cmp_lt_f32_e64 s[2:3], 0, v145
	s_nop 1
	v_cndmask_b32_e64 v145, v148, v149, s[2:3]
	v_mul_f32_e32 v148, 0x37800000, v145
	v_cndmask_b32_e32 v145, v145, v148, vcc
	v_cmp_class_f32_e32 vcc, v144, v196
	s_nop 1
	v_cndmask_b32_e32 v144, v145, v144, vcc
	v_div_scale_f32 v145, s[2:3], v144, v144, 1.0
	v_rcp_f32_e32 v148, v145
	s_nop 0
	v_fma_f32 v149, -v145, v148, 1.0
	v_fmac_f32_e32 v148, v149, v148
	v_div_scale_f32 v149, vcc, 1.0, v144, 1.0
	v_mul_f32_e32 v150, v149, v148
	v_fma_f32 v151, -v145, v150, v149
	v_fmac_f32_e32 v150, v151, v148
	v_fma_f32 v145, -v145, v150, v149
	v_div_fmas_f32 v145, v145, v148, v150
	v_div_fixup_f32 v144, v145, v144, 1.0
	global_load_dword v145, v[146:147], off offset:20
	v_mov_b32_e32 v148, 0x358637bd
	s_waitcnt vmcnt(0)
	v_cvt_f32_u32_e32 v145, v145
	v_fmac_f32_e32 v148, 0x36800000, v145
	v_cmp_gt_f32_e32 vcc, s66, v148
	v_mul_f32_e32 v145, 0x4f800000, v148
	s_nop 0
	v_cndmask_b32_e32 v145, v148, v145, vcc
	v_sqrt_f32_e32 v148, v145
	s_nop 0
	v_add_u32_e32 v149, -1, v148
	v_fma_f32 v150, -v149, v148, v145
	v_cmp_ge_f32_e64 s[2:3], 0, v150
	v_add_u32_e32 v150, 1, v148
	s_nop 0
	v_cndmask_b32_e64 v149, v148, v149, s[2:3]
	v_fma_f32 v148, -v150, v148, v145
	v_cmp_lt_f32_e64 s[2:3], 0, v148
	s_nop 1
	v_cndmask_b32_e64 v148, v149, v150, s[2:3]
	v_mul_f32_e32 v149, 0x37800000, v148
	v_cndmask_b32_e32 v148, v148, v149, vcc
	v_cmp_class_f32_e32 vcc, v145, v196
	s_nop 1
	v_cndmask_b32_e32 v145, v148, v145, vcc
	v_div_scale_f32 v148, s[2:3], v145, v145, 1.0
	v_rcp_f32_e32 v149, v148
	s_nop 0
	v_fma_f32 v150, -v148, v149, 1.0
	v_fmac_f32_e32 v149, v150, v149
	v_div_scale_f32 v150, vcc, 1.0, v145, 1.0
	v_mul_f32_e32 v151, v150, v149
	v_fma_f32 v152, -v148, v151, v150
	v_fmac_f32_e32 v151, v152, v149
	v_fma_f32 v148, -v148, v151, v150
	v_div_fmas_f32 v148, v148, v149, v151
	v_div_fixup_f32 v145, v148, v145, 1.0
	global_load_dword v148, v[146:147], off offset:24
	v_mov_b32_e32 v149, 0x358637bd
	s_waitcnt vmcnt(0)
	v_cvt_f32_u32_e32 v148, v148
	v_fmac_f32_e32 v149, 0x36800000, v148
	v_cmp_gt_f32_e32 vcc, s66, v149
	v_mul_f32_e32 v148, 0x4f800000, v149
	s_nop 0
	v_cndmask_b32_e32 v148, v149, v148, vcc
	v_sqrt_f32_e32 v149, v148
	s_nop 0
	v_add_u32_e32 v150, -1, v149
	v_fma_f32 v151, -v150, v149, v148
	v_cmp_ge_f32_e64 s[2:3], 0, v151
	v_add_u32_e32 v151, 1, v149
	s_nop 0
	v_cndmask_b32_e64 v150, v149, v150, s[2:3]
	v_fma_f32 v149, -v151, v149, v148
	v_cmp_lt_f32_e64 s[2:3], 0, v149
	s_nop 1
	v_cndmask_b32_e64 v149, v150, v151, s[2:3]
	v_mul_f32_e32 v150, 0x37800000, v149
	v_cndmask_b32_e32 v149, v149, v150, vcc
	v_cmp_class_f32_e32 vcc, v148, v196
	s_nop 1
	v_cndmask_b32_e32 v148, v149, v148, vcc
	v_div_scale_f32 v149, s[2:3], v148, v148, 1.0
	v_rcp_f32_e32 v150, v149
	s_nop 0
	v_fma_f32 v151, -v149, v150, 1.0
	v_fmac_f32_e32 v150, v151, v150
	v_div_scale_f32 v151, vcc, 1.0, v148, 1.0
	v_mul_f32_e32 v152, v151, v150
	v_fma_f32 v153, -v149, v152, v151
	v_fmac_f32_e32 v152, v153, v150
	v_fma_f32 v149, -v149, v152, v151
	v_div_fmas_f32 v149, v149, v150, v152
	v_div_fixup_f32 v148, v149, v148, 1.0
	global_load_dword v149, v[146:147], off offset:28
	v_mov_b32_e32 v150, 0x358637bd
	s_waitcnt vmcnt(0)
	v_cvt_f32_u32_e32 v149, v149
	v_fmac_f32_e32 v150, 0x36800000, v149
	v_cmp_gt_f32_e32 vcc, s66, v150
	v_mul_f32_e32 v149, 0x4f800000, v150
	s_nop 0
	v_cndmask_b32_e32 v149, v150, v149, vcc
	v_sqrt_f32_e32 v150, v149
	s_nop 0
	v_add_u32_e32 v151, -1, v150
	v_fma_f32 v152, -v151, v150, v149
	v_cmp_ge_f32_e64 s[2:3], 0, v152
	v_add_u32_e32 v152, 1, v150
	s_nop 0
	v_cndmask_b32_e64 v151, v150, v151, s[2:3]
	v_fma_f32 v150, -v152, v150, v149
	v_cmp_lt_f32_e64 s[2:3], 0, v150
	s_nop 1
	v_cndmask_b32_e64 v150, v151, v152, s[2:3]
	v_mul_f32_e32 v151, 0x37800000, v150
	v_cndmask_b32_e32 v150, v150, v151, vcc
	v_cmp_class_f32_e32 vcc, v149, v196
	s_nop 1
	v_cndmask_b32_e32 v149, v150, v149, vcc
	v_div_scale_f32 v150, s[2:3], v149, v149, 1.0
	v_rcp_f32_e32 v151, v150
	s_nop 0
	v_fma_f32 v152, -v150, v151, 1.0
	v_fmac_f32_e32 v151, v152, v151
	v_div_scale_f32 v152, vcc, 1.0, v149, 1.0
	v_mul_f32_e32 v153, v152, v151
	v_fma_f32 v154, -v150, v153, v152
	v_fmac_f32_e32 v153, v154, v151
	v_fma_f32 v150, -v150, v153, v152
	v_div_fmas_f32 v150, v150, v151, v153
	v_div_fixup_f32 v149, v150, v149, 1.0
	global_load_dword v150, v[146:147], off offset:512
	v_mov_b32_e32 v151, 0x358637bd
	s_waitcnt vmcnt(0)
	v_cvt_f32_u32_e32 v150, v150
	v_fmac_f32_e32 v151, 0x36800000, v150
	v_cmp_gt_f32_e32 vcc, s66, v151
	v_mul_f32_e32 v150, 0x4f800000, v151
	s_nop 0
	v_cndmask_b32_e32 v150, v151, v150, vcc
	v_sqrt_f32_e32 v151, v150
	s_nop 0
	v_add_u32_e32 v152, -1, v151
	v_fma_f32 v153, -v152, v151, v150
	v_cmp_ge_f32_e64 s[2:3], 0, v153
	v_add_u32_e32 v153, 1, v151
	s_nop 0
	v_cndmask_b32_e64 v152, v151, v152, s[2:3]
	v_fma_f32 v151, -v153, v151, v150
	v_cmp_lt_f32_e64 s[2:3], 0, v151
	s_nop 1
	v_cndmask_b32_e64 v151, v152, v153, s[2:3]
	v_mul_f32_e32 v152, 0x37800000, v151
	v_cndmask_b32_e32 v151, v151, v152, vcc
	v_cmp_class_f32_e32 vcc, v150, v196
	s_nop 1
	v_cndmask_b32_e32 v150, v151, v150, vcc
	v_div_scale_f32 v151, s[2:3], v150, v150, 1.0
	v_rcp_f32_e32 v152, v151
	s_nop 0
	v_fma_f32 v153, -v151, v152, 1.0
	v_fmac_f32_e32 v152, v153, v152
	v_div_scale_f32 v153, vcc, 1.0, v150, 1.0
	v_mul_f32_e32 v154, v153, v152
	v_fma_f32 v155, -v151, v154, v153
	v_fmac_f32_e32 v154, v155, v152
	v_fma_f32 v151, -v151, v154, v153
	v_div_fmas_f32 v151, v151, v152, v154
	v_div_fixup_f32 v150, v151, v150, 1.0
	global_load_dword v151, v[146:147], off offset:516
	v_mov_b32_e32 v152, 0x358637bd
	s_waitcnt vmcnt(0)
; __device__ __forceinline__ float rms_r(ssq_t ssq) { float eps = RMS_EPS; asm volatile("" : "+v"(eps));
;     return 1.f / sqrtf(fmaf((float)ssq, 1.f / (SSQ_ONE * D), eps)); }
;     __device__ __forceinline__ void operator()(const Acc& acc, const Unit& u, int wr, int wc, int fr, int fq) const {
;     ...
;         for (int bj = 0; bj < 2; ++bj)
; #pragma unroll
;             for (int n = 0; n < 2; ++n) { const ssq_t* s = ssq + col0 + bj * HALF + 4 * n; rv[bj][n] = (f32x4){rms_r(s[0]), rms_r(s[1]), rms_r(s[2]), rms_r(s[3])}; }
	v_cvt_f32_u32_e32 v151, v151
	v_fmac_f32_e32 v152, 0x36800000, v151
	v_cmp_gt_f32_e32 vcc, s66, v152
	v_mul_f32_e32 v151, 0x4f800000, v152
	s_nop 0
	v_cndmask_b32_e32 v151, v152, v151, vcc
	v_sqrt_f32_e32 v152, v151
	s_nop 0
	v_add_u32_e32 v153, -1, v152
	v_fma_f32 v154, -v153, v152, v151
	v_cmp_ge_f32_e64 s[2:3], 0, v154
	v_add_u32_e32 v154, 1, v152
	s_nop 0
	v_cndmask_b32_e64 v153, v152, v153, s[2:3]
	v_fma_f32 v152, -v154, v152, v151
	v_cmp_lt_f32_e64 s[2:3], 0, v152
	s_nop 1
	v_cndmask_b32_e64 v152, v153, v154, s[2:3]
	v_mul_f32_e32 v153, 0x37800000, v152
	v_cndmask_b32_e32 v152, v152, v153, vcc
	v_cmp_class_f32_e32 vcc, v151, v196
	s_nop 1
	v_cndmask_b32_e32 v151, v152, v151, vcc
	v_div_scale_f32 v152, s[2:3], v151, v151, 1.0
	v_rcp_f32_e32 v153, v152
	s_nop 0
	v_fma_f32 v154, -v152, v153, 1.0
	v_fmac_f32_e32 v153, v154, v153
	v_div_scale_f32 v154, vcc, 1.0, v151, 1.0
	v_mul_f32_e32 v155, v154, v153
	v_fma_f32 v156, -v152, v155, v154
	v_fmac_f32_e32 v155, v156, v153
	v_fma_f32 v152, -v152, v155, v154
	v_div_fmas_f32 v152, v152, v153, v155
	v_div_fixup_f32 v151, v152, v151, 1.0
	global_load_dword v152, v[146:147], off offset:520
	v_mov_b32_e32 v153, 0x358637bd
	s_waitcnt vmcnt(0)
	v_cvt_f32_u32_e32 v152, v152
	v_fmac_f32_e32 v153, 0x36800000, v152
	v_cmp_gt_f32_e32 vcc, s66, v153
	v_mul_f32_e32 v152, 0x4f800000, v153
	s_nop 0
	v_cndmask_b32_e32 v152, v153, v152, vcc
	v_sqrt_f32_e32 v153, v152
	s_nop 0
	v_add_u32_e32 v154, -1, v153
	v_fma_f32 v155, -v154, v153, v152
	v_cmp_ge_f32_e64 s[2:3], 0, v155
	v_add_u32_e32 v155, 1, v153
	s_nop 0
	v_cndmask_b32_e64 v154, v153, v154, s[2:3]
	v_fma_f32 v153, -v155, v153, v152
	v_cmp_lt_f32_e64 s[2:3], 0, v153
	s_nop 1
	v_cndmask_b32_e64 v153, v154, v155, s[2:3]
	v_mul_f32_e32 v154, 0x37800000, v153
	v_cndmask_b32_e32 v153, v153, v154, vcc
	v_cmp_class_f32_e32 vcc, v152, v196
	s_nop 1
	v_cndmask_b32_e32 v152, v153, v152, vcc
	v_div_scale_f32 v153, s[2:3], v152, v152, 1.0
	v_rcp_f32_e32 v154, v153
	s_nop 0
	v_fma_f32 v155, -v153, v154, 1.0
	v_fmac_f32_e32 v154, v155, v154
	v_div_scale_f32 v155, vcc, 1.0, v152, 1.0
	v_mul_f32_e32 v156, v155, v154
	v_fma_f32 v157, -v153, v156, v155
	v_fmac_f32_e32 v156, v157, v154
	v_fma_f32 v153, -v153, v156, v155
	v_div_fmas_f32 v153, v153, v154, v156
	v_div_fixup_f32 v152, v153, v152, 1.0
	global_load_dword v153, v[146:147], off offset:524
	v_mov_b32_e32 v154, 0x358637bd
	s_waitcnt vmcnt(0)
	v_cvt_f32_u32_e32 v153, v153
	v_fmac_f32_e32 v154, 0x36800000, v153
	v_cmp_gt_f32_e32 vcc, s66, v154
	v_mul_f32_e32 v153, 0x4f800000, v154
	s_nop 0
	v_cndmask_b32_e32 v153, v154, v153, vcc
	v_sqrt_f32_e32 v154, v153
	s_nop 0
	v_add_u32_e32 v155, -1, v154
	v_fma_f32 v156, -v155, v154, v153
	v_cmp_ge_f32_e64 s[2:3], 0, v156
	v_add_u32_e32 v156, 1, v154
	s_nop 0
	v_cndmask_b32_e64 v155, v154, v155, s[2:3]
	v_fma_f32 v154, -v156, v154, v153
	v_cmp_lt_f32_e64 s[2:3], 0, v154
	s_nop 1
	v_cndmask_b32_e64 v154, v155, v156, s[2:3]
	v_mul_f32_e32 v155, 0x37800000, v154
	v_cndmask_b32_e32 v154, v154, v155, vcc
	v_cmp_class_f32_e32 vcc, v153, v196
	s_nop 1
	v_cndmask_b32_e32 v153, v154, v153, vcc
	v_div_scale_f32 v154, s[2:3], v153, v153, 1.0
	v_rcp_f32_e32 v155, v154
	s_nop 0
	v_fma_f32 v156, -v154, v155, 1.0
	v_fmac_f32_e32 v155, v156, v155
	v_div_scale_f32 v156, vcc, 1.0, v153, 1.0
	v_mul_f32_e32 v157, v156, v155
	v_fma_f32 v158, -v154, v157, v156
	v_fmac_f32_e32 v157, v158, v155
	v_fma_f32 v154, -v154, v157, v156
	v_div_fmas_f32 v154, v154, v155, v157
	v_div_fixup_f32 v153, v154, v153, 1.0
	global_load_dword v154, v[146:147], off offset:528
	v_mov_b32_e32 v155, 0x358637bd
	s_waitcnt vmcnt(0)
	v_cvt_f32_u32_e32 v154, v154
	v_fmac_f32_e32 v155, 0x36800000, v154
	v_cmp_gt_f32_e32 vcc, s66, v155
	v_mul_f32_e32 v154, 0x4f800000, v155
	s_nop 0
	v_cndmask_b32_e32 v154, v155, v154, vcc
	v_sqrt_f32_e32 v155, v154
	s_nop 0
	v_add_u32_e32 v156, -1, v155
	v_fma_f32 v157, -v156, v155, v154
	v_cmp_ge_f32_e64 s[2:3], 0, v157
	v_add_u32_e32 v157, 1, v155
	s_nop 0
	v_cndmask_b32_e64 v156, v155, v156, s[2:3]
	v_fma_f32 v155, -v157, v155, v154
	v_cmp_lt_f32_e64 s[2:3], 0, v155
	s_nop 1
	v_cndmask_b32_e64 v155, v156, v157, s[2:3]
	v_mul_f32_e32 v156, 0x37800000, v155
	v_cndmask_b32_e32 v155, v155, v156, vcc
	v_cmp_class_f32_e32 vcc, v154, v196
	s_nop 1
	v_cndmask_b32_e32 v154, v155, v154, vcc
	v_div_scale_f32 v155, s[2:3], v154, v154, 1.0
	v_rcp_f32_e32 v156, v155
	s_nop 0
	v_fma_f32 v157, -v155, v156, 1.0
	v_fmac_f32_e32 v156, v157, v156
	v_div_scale_f32 v157, vcc, 1.0, v154, 1.0
	v_mul_f32_e32 v158, v157, v156
	v_fma_f32 v159, -v155, v158, v157
	v_fmac_f32_e32 v158, v159, v156
	v_fma_f32 v155, -v155, v158, v157
	v_div_fmas_f32 v155, v155, v156, v158
	v_div_fixup_f32 v154, v155, v154, 1.0
	global_load_dword v155, v[146:147], off offset:532
	v_mov_b32_e32 v156, 0x358637bd
	s_waitcnt vmcnt(0)
	v_cvt_f32_u32_e32 v155, v155
	v_fmac_f32_e32 v156, 0x36800000, v155
	v_cmp_gt_f32_e32 vcc, s66, v156
	v_mul_f32_e32 v155, 0x4f800000, v156
	s_nop 0
	v_cndmask_b32_e32 v155, v156, v155, vcc
	v_sqrt_f32_e32 v156, v155
	s_nop 0
	v_add_u32_e32 v157, -1, v156
	v_fma_f32 v158, -v157, v156, v155
	v_cmp_ge_f32_e64 s[2:3], 0, v158
	v_add_u32_e32 v158, 1, v156
	s_nop 0
	v_cndmask_b32_e64 v157, v156, v157, s[2:3]
	v_fma_f32 v156, -v158, v156, v155
	v_cmp_lt_f32_e64 s[2:3], 0, v156
	s_nop 1
	v_cndmask_b32_e64 v156, v157, v158, s[2:3]
	v_mul_f32_e32 v157, 0x37800000, v156
	v_cndmask_b32_e32 v156, v156, v157, vcc
	v_cmp_class_f32_e32 vcc, v155, v196
	s_nop 1
	v_cndmask_b32_e32 v155, v156, v155, vcc
	v_div_scale_f32 v156, s[2:3], v155, v155, 1.0
	v_rcp_f32_e32 v157, v156
	s_nop 0
	v_fma_f32 v158, -v156, v157, 1.0
	v_fmac_f32_e32 v157, v158, v157
	v_div_scale_f32 v158, vcc, 1.0, v155, 1.0
	v_mul_f32_e32 v159, v158, v157
	v_fma_f32 v160, -v156, v159, v158
	v_fmac_f32_e32 v159, v160, v157
	v_fma_f32 v156, -v156, v159, v158
	v_div_fmas_f32 v156, v156, v157, v159
	v_div_fixup_f32 v155, v156, v155, 1.0
	global_load_dword v156, v[146:147], off offset:536
	v_mov_b32_e32 v157, 0x358637bd
	global_load_dword v146, v[146:147], off offset:540
	v_mov_b32_e32 v147, 0x358637bd
	s_waitcnt vmcnt(1)
; __device__ __forceinline__ unsigned cvt_pk_bf16(float lo, float hi) { unsigned r; asm("v_cvt_pk_bf16_f32 %0, %1, %2" : "=v"(r) : "v"(lo), "v"(hi)); return r; }
;     __device__ __forceinline__ void operator()(const Acc& acc, const Unit& u, int wr, int wc, int fr, int fq) const {
;     ...
;             for (int n = 0; n < 2; ++n) { const ssq_t* s = ssq + col0 + bj * HALF + 4 * n; rv[bj][n] = (f32x4){rms_r(s[0]), rms_r(s[1]), rms_r(s[2]), rms_r(s[3])}; }
;         float brv[8];
; #pragma unroll
;         for (int q = 0; q < 8; ++q) brv[q] = bias[row0 + (q >> 2) * HALF + (q & 3) * 16];
; #pragma unroll
;         for (int ai = 0; ai < 2; ++ai)
; #pragma unroll
;             for (int m = 0; m < 4; ++m) {
;                 const int row = row0 + ai * HALF + m * 16;
;                 const float br = brv[ai * 4 + m];
;                 bf16_t* rowp = O + (size_t)row * NTOK + col0;
; #pragma unroll
;                 for (int bj = 0; bj < 2; ++bj) {
;                     const f32x4 v0 = acc[ai][bj][m][0] * rv[bj][0] + br, v1 = acc[ai][bj][m][1] * rv[bj][1] + br;
;                     u32x4 w; w.x = cvt_pk_bf16(v0[0], v0[1]); w.y = cvt_pk_bf16(v0[2], v0[3]); w.z = cvt_pk_bf16(v1[0], v1[1]); w.w = cvt_pk_bf16(v1[2], v1[3]);
;                     *(u32x4*)(rowp + bj * HALF) = w;
	v_cvt_f32_u32_e32 v156, v156
	s_waitcnt vmcnt(0)
	v_cvt_f32_u32_e32 v146, v146
	v_fmac_f32_e32 v157, 0x36800000, v156
	v_cmp_gt_f32_e32 vcc, s66, v157
	v_mul_f32_e32 v156, 0x4f800000, v157
	v_fmac_f32_e32 v147, 0x36800000, v146
	v_cndmask_b32_e32 v156, v157, v156, vcc
	v_sqrt_f32_e32 v157, v156
	v_mul_f32_e32 v146, 0x4f800000, v147
	v_add_u32_e32 v158, -1, v157
	v_fma_f32 v159, -v158, v157, v156
	v_cmp_ge_f32_e64 s[2:3], 0, v159
	v_add_u32_e32 v159, 1, v157
	s_nop 0
	v_cndmask_b32_e64 v158, v157, v158, s[2:3]
	v_fma_f32 v157, -v159, v157, v156
	v_cmp_lt_f32_e64 s[2:3], 0, v157
	s_nop 1
	v_cndmask_b32_e64 v157, v158, v159, s[2:3]
	v_mul_f32_e32 v158, 0x37800000, v157
	v_cndmask_b32_e32 v157, v157, v158, vcc
	v_cmp_class_f32_e32 vcc, v156, v196
	s_nop 1
	v_cndmask_b32_e32 v156, v157, v156, vcc
	v_div_scale_f32 v157, s[2:3], v156, v156, 1.0
	v_rcp_f32_e32 v158, v157
	s_nop 0
	v_fma_f32 v159, -v157, v158, 1.0
	v_fmac_f32_e32 v158, v159, v158
	v_div_scale_f32 v159, vcc, 1.0, v156, 1.0
	v_mul_f32_e32 v160, v159, v158
	v_fma_f32 v162, -v157, v160, v159
	v_fmac_f32_e32 v160, v162, v158
	v_fma_f32 v157, -v157, v160, v159
	v_div_fmas_f32 v157, v157, v158, v160
	v_cmp_gt_f32_e32 vcc, s66, v147
	v_div_fixup_f32 v156, v157, v156, 1.0
	s_nop 0
	v_cndmask_b32_e32 v146, v147, v146, vcc
	v_sqrt_f32_e32 v147, v146
	s_nop 0
	v_add_u32_e32 v157, -1, v147
	v_fma_f32 v158, -v157, v147, v146
	v_cmp_ge_f32_e64 s[2:3], 0, v158
	v_add_u32_e32 v158, 1, v147
	s_nop 0
	v_cndmask_b32_e64 v157, v147, v157, s[2:3]
	v_fma_f32 v147, -v158, v147, v146
	v_cmp_lt_f32_e64 s[2:3], 0, v147
	s_nop 1
	v_cndmask_b32_e64 v147, v157, v158, s[2:3]
	v_mul_f32_e32 v157, 0x37800000, v147
	v_cndmask_b32_e32 v147, v147, v157, vcc
	v_cmp_class_f32_e32 vcc, v146, v196
	s_nop 1
	v_cndmask_b32_e32 v146, v147, v146, vcc
	v_div_scale_f32 v147, s[2:3], v146, v146, 1.0
	v_rcp_f32_e32 v157, v147
	s_nop 0
	v_fma_f32 v158, -v147, v157, 1.0
	v_fmac_f32_e32 v157, v158, v157
	v_div_scale_f32 v158, vcc, 1.0, v146, 1.0
	v_mul_f32_e32 v159, v158, v157
	v_fma_f32 v160, -v147, v159, v158
	v_fmac_f32_e32 v159, v160, v157
	v_fma_f32 v147, -v147, v159, v158
	v_lshl_add_u32 v158, s0, 8, v161
	v_div_fmas_f32 v147, v147, v157, v159
	v_ashrrev_i32_e32 v159, 31, v158
	v_div_fixup_f32 v157, v147, v146, 1.0
	v_lshl_add_u64 v[146:147], v[158:159], 2, s[12:13]
	global_load_dword v164, v[146:147], off
	global_load_dword v166, v[146:147], off offset:64
	global_load_dword v170, v[146:147], off offset:128
	global_load_dword v172, v[146:147], off offset:192
	global_load_dword v168, v[146:147], off offset:512
	global_load_dword v162, v[146:147], off offset:576
	global_load_dword v160, v[146:147], off offset:640
	s_nop 0
	global_load_dword v146, v[146:147], off offset:704
	v_lshlrev_b64 v[174:175], 14, v[158:159]
	v_lshl_add_u64 v[174:175], s[10:11], 0, v[174:175]
	v_lshl_add_u64 v[142:143], v[174:175], 0, v[178:179]
	s_mov_b64 s[0:1], 0x200000
	s_waitcnt vmcnt(7)
	v_pk_fma_f32 v[126:127], v[126:127], v[140:141], v[164:165] op_sel_hi:[1,1,0]
	v_pk_fma_f32 v[124:125], v[124:125], v[138:139], v[164:165] op_sel_hi:[1,1,0]
	v_pk_fma_f32 v[174:175], v[122:123], v[148:149], v[164:165] op_sel_hi:[1,1,0]
	v_pk_fma_f32 v[122:123], v[120:121], v[144:145], v[164:165] op_sel_hi:[1,1,0]
	v_cvt_pk_bf16_f32 v120, v124, v125
	v_cvt_pk_bf16_f32 v121, v126, v127
	v_pk_fma_f32 v[116:117], v[116:117], v[150:151], v[164:165] op_sel_hi:[1,1,0]
	v_cvt_pk_bf16_f32 v122, v122, v123
	v_cvt_pk_bf16_f32 v123, v174, v175
	global_store_dwordx4 v[142:143], v[120:123], off sc0 sc1
	v_pk_fma_f32 v[118:119], v[118:119], v[152:153], v[164:165] op_sel_hi:[1,1,0]
	s_waitcnt vmcnt(7)
	v_pk_fma_f32 v[110:111], v[110:111], v[140:141], v[166:167] op_sel_hi:[1,1,0]
	v_pk_fma_f32 v[120:121], v[114:115], v[156:157], v[164:165] op_sel_hi:[1,1,0]
	v_pk_fma_f32 v[114:115], v[112:113], v[154:155], v[164:165] op_sel_hi:[1,1,0]
	v_cvt_pk_bf16_f32 v112, v116, v117
	v_cvt_pk_bf16_f32 v113, v118, v119
	v_pk_fma_f32 v[108:109], v[108:109], v[138:139], v[166:167] op_sel_hi:[1,1,0]
	v_cvt_pk_bf16_f32 v114, v114, v115
	v_cvt_pk_bf16_f32 v115, v120, v121
	global_store_dwordx4 v[142:143], v[112:115], off offset:256 sc0 sc1
	v_pk_fma_f32 v[100:101], v[100:101], v[150:151], v[166:167] op_sel_hi:[1,1,0]
	v_pk_fma_f32 v[102:103], v[102:103], v[152:153], v[166:167] op_sel_hi:[1,1,0]
	v_or_b32_e32 v112, 16, v158
	v_ashrrev_i32_e32 v113, 31, v112
	v_lshlrev_b64 v[112:113], 14, v[112:113]
	v_lshl_add_u64 v[112:113], s[10:11], 0, v[112:113]
	v_lshl_add_u64 v[112:113], v[112:113], 0, v[178:179]
	v_pk_fma_f32 v[114:115], v[106:107], v[148:149], v[166:167] op_sel_hi:[1,1,0]
	v_pk_fma_f32 v[106:107], v[104:105], v[144:145], v[166:167] op_sel_hi:[1,1,0]
	v_cvt_pk_bf16_f32 v104, v108, v109
	v_cvt_pk_bf16_f32 v105, v110, v111
	s_waitcnt vmcnt(7)
	v_pk_fma_f32 v[94:95], v[94:95], v[140:141], v[170:171] op_sel_hi:[1,1,0]
	v_cvt_pk_bf16_f32 v106, v106, v107
	v_cvt_pk_bf16_f32 v107, v114, v115
	global_store_dwordx4 v[112:113], v[104:107], off sc0 sc1
	v_pk_fma_f32 v[92:93], v[92:93], v[138:139], v[170:171] op_sel_hi:[1,1,0]
	v_pk_fma_f32 v[84:85], v[84:85], v[150:151], v[170:171] op_sel_hi:[1,1,0]
	v_pk_fma_f32 v[104:105], v[98:99], v[156:157], v[166:167] op_sel_hi:[1,1,0]
	v_pk_fma_f32 v[98:99], v[96:97], v[154:155], v[166:167] op_sel_hi:[1,1,0]
	v_cvt_pk_bf16_f32 v96, v100, v101
	v_cvt_pk_bf16_f32 v97, v102, v103
	v_pk_fma_f32 v[86:87], v[86:87], v[152:153], v[170:171] op_sel_hi:[1,1,0]
	v_cvt_pk_bf16_f32 v98, v98, v99
	v_cvt_pk_bf16_f32 v99, v104, v105
	global_store_dwordx4 v[112:113], v[96:99], off offset:256 sc0 sc1
	s_waitcnt vmcnt(8)
; __device__ __forceinline__ unsigned cvt_pk_bf16(float lo, float hi) { unsigned r; asm("v_cvt_pk_bf16_f32 %0, %1, %2" : "=v"(r) : "v"(lo), "v"(hi)); return r; }
;     __device__ __forceinline__ void operator()(const Acc& acc, const Unit& u, int wr, int wc, int fr, int fq) const {
;     ...
; #pragma unroll
;         for (int ai = 0; ai < 2; ++ai)
; #pragma unroll
;             for (int m = 0; m < 4; ++m) {
;                 const int row = row0 + ai * HALF + m * 16;
;                 const float br = brv[ai * 4 + m];
;                 bf16_t* rowp = O + (size_t)row * NTOK + col0;
; #pragma unroll
;                 for (int bj = 0; bj < 2; ++bj) {
;                     const f32x4 v0 = acc[ai][bj][m][0] * rv[bj][0] + br, v1 = acc[ai][bj][m][1] * rv[bj][1] + br;
;                     u32x4 w; w.x = cvt_pk_bf16(v0[0], v0[1]); w.y = cvt_pk_bf16(v0[2], v0[3]); w.z = cvt_pk_bf16(v1[0], v1[1]); w.w = cvt_pk_bf16(v1[2], v1[3]);
;                     *(u32x4*)(rowp + bj * HALF) = w;
	v_pk_fma_f32 v[78:79], v[78:79], v[140:141], v[172:173] op_sel_hi:[1,1,0]
	v_pk_fma_f32 v[76:77], v[76:77], v[138:139], v[172:173] op_sel_hi:[1,1,0]
	v_or_b32_e32 v96, 32, v158
	v_ashrrev_i32_e32 v97, 31, v96
	v_lshlrev_b64 v[96:97], 14, v[96:97]
	v_lshl_add_u64 v[96:97], s[10:11], 0, v[96:97]
	v_lshl_add_u64 v[96:97], v[96:97], 0, v[178:179]
	v_pk_fma_f32 v[98:99], v[90:91], v[148:149], v[170:171] op_sel_hi:[1,1,0]
	v_pk_fma_f32 v[90:91], v[88:89], v[144:145], v[170:171] op_sel_hi:[1,1,0]
	v_cvt_pk_bf16_f32 v88, v92, v93
	v_cvt_pk_bf16_f32 v89, v94, v95
	v_pk_fma_f32 v[70:71], v[70:71], v[152:153], v[172:173] op_sel_hi:[1,1,0]
	v_cvt_pk_bf16_f32 v90, v90, v91
	v_cvt_pk_bf16_f32 v91, v98, v99
	global_store_dwordx4 v[96:97], v[88:91], off sc0 sc1
	v_pk_fma_f32 v[68:69], v[68:69], v[150:151], v[172:173] op_sel_hi:[1,1,0]
	s_waitcnt vmcnt(8)
	v_pk_fma_f32 v[60:61], v[60:61], v[138:139], v[168:169] op_sel_hi:[1,1,0]
	v_pk_fma_f32 v[88:89], v[82:83], v[156:157], v[170:171] op_sel_hi:[1,1,0]
	v_pk_fma_f32 v[82:83], v[80:81], v[154:155], v[170:171] op_sel_hi:[1,1,0]
	v_cvt_pk_bf16_f32 v80, v84, v85
	v_cvt_pk_bf16_f32 v81, v86, v87
	v_pk_fma_f32 v[62:63], v[62:63], v[140:141], v[168:169] op_sel_hi:[1,1,0]
	v_cvt_pk_bf16_f32 v82, v82, v83
	v_cvt_pk_bf16_f32 v83, v88, v89
	global_store_dwordx4 v[96:97], v[80:83], off offset:256 sc0 sc1
	v_pk_fma_f32 v[54:55], v[54:55], v[152:153], v[168:169] op_sel_hi:[1,1,0]
	v_pk_fma_f32 v[52:53], v[52:53], v[150:151], v[168:169] op_sel_hi:[1,1,0]
	v_or_b32_e32 v80, 48, v158
	v_ashrrev_i32_e32 v81, 31, v80
	v_lshlrev_b64 v[80:81], 14, v[80:81]
	v_lshl_add_u64 v[80:81], s[10:11], 0, v[80:81]
	v_lshl_add_u64 v[80:81], v[80:81], 0, v[178:179]
	v_pk_fma_f32 v[82:83], v[74:75], v[148:149], v[172:173] op_sel_hi:[1,1,0]
	v_pk_fma_f32 v[74:75], v[72:73], v[144:145], v[172:173] op_sel_hi:[1,1,0]
	v_cvt_pk_bf16_f32 v72, v76, v77
	v_cvt_pk_bf16_f32 v73, v78, v79
	s_waitcnt vmcnt(8)
	v_pk_fma_f32 v[48:49], v[48:49], v[138:139], v[162:163] op_sel_hi:[1,1,0]
	v_cvt_pk_bf16_f32 v74, v74, v75
	v_cvt_pk_bf16_f32 v75, v82, v83
	global_store_dwordx4 v[80:81], v[72:75], off sc0 sc1
	v_pk_fma_f32 v[38:39], v[38:39], v[152:153], v[162:163] op_sel_hi:[1,1,0]
	v_pk_fma_f32 v[36:37], v[36:37], v[150:151], v[162:163] op_sel_hi:[1,1,0]
	v_pk_fma_f32 v[72:73], v[66:67], v[156:157], v[172:173] op_sel_hi:[1,1,0]
	v_pk_fma_f32 v[66:67], v[64:65], v[154:155], v[172:173] op_sel_hi:[1,1,0]
	v_cvt_pk_bf16_f32 v64, v68, v69
	v_cvt_pk_bf16_f32 v65, v70, v71
	s_waitcnt vmcnt(8)
	v_pk_fma_f32 v[32:33], v[32:33], v[138:139], v[160:161] op_sel_hi:[1,1,0]
	v_cvt_pk_bf16_f32 v66, v66, v67
	v_cvt_pk_bf16_f32 v67, v72, v73
	global_store_dwordx4 v[80:81], v[64:67], off offset:256 sc0 sc1
	v_pk_fma_f32 v[22:23], v[22:23], v[152:153], v[160:161] op_sel_hi:[1,1,0]
	v_pk_fma_f32 v[20:21], v[20:21], v[150:151], v[160:161] op_sel_hi:[1,1,0]
	v_lshl_add_u64 v[64:65], v[142:143], 0, s[0:1]
	s_mov_b32 s0, 0x200000
	v_pk_fma_f32 v[66:67], v[58:59], v[148:149], v[168:169] op_sel_hi:[1,1,0]
	v_pk_fma_f32 v[58:59], v[56:57], v[144:145], v[168:169] op_sel_hi:[1,1,0]
	v_cvt_pk_bf16_f32 v56, v60, v61
	v_add_co_u32_e32 v60, vcc, s0, v142
	v_cvt_pk_bf16_f32 v57, v62, v63
	v_cvt_pk_bf16_f32 v58, v58, v59
	v_cvt_pk_bf16_f32 v59, v66, v67
	s_mov_b64 s[0:1], 0x240000
	s_nop 0
	v_addc_co_u32_e32 v61, vcc, 0, v143, vcc
	global_store_dwordx4 v[60:61], v[56:59], off sc0 sc1
	s_waitcnt vmcnt(9)
	v_pk_fma_f32 v[16:17], v[16:17], v[138:139], v[146:147] op_sel_hi:[1,1,0]
	v_pk_fma_f32 v[6:7], v[6:7], v[152:153], v[146:147] op_sel_hi:[1,1,0]
	v_pk_fma_f32 v[56:57], v[46:47], v[156:157], v[168:169] op_sel_hi:[1,1,0]
	v_pk_fma_f32 v[46:47], v[44:45], v[154:155], v[168:169] op_sel_hi:[1,1,0]
	v_cvt_pk_bf16_f32 v44, v52, v53
	v_cvt_pk_bf16_f32 v45, v54, v55
	v_pk_fma_f32 v[4:5], v[4:5], v[150:151], v[146:147] op_sel_hi:[1,1,0]
	v_cvt_pk_bf16_f32 v46, v46, v47
	v_cvt_pk_bf16_f32 v47, v56, v57
	global_store_dwordx4 v[64:65], v[44:47], off offset:256 sc0 sc1
	s_nop 1
	v_lshl_add_u64 v[44:45], v[142:143], 0, s[0:1]
	v_pk_fma_f32 v[46:47], v[50:51], v[140:141], v[162:163] op_sel_hi:[1,1,0]
	s_mov_b32 s0, 0x240000
	v_pk_fma_f32 v[50:51], v[42:43], v[148:149], v[162:163] op_sel_hi:[1,1,0]
	v_pk_fma_f32 v[42:43], v[40:41], v[144:145], v[162:163] op_sel_hi:[1,1,0]
	v_cvt_pk_bf16_f32 v41, v46, v47
	v_add_co_u32_e32 v46, vcc, s0, v142
	v_cvt_pk_bf16_f32 v40, v48, v49
	v_cvt_pk_bf16_f32 v42, v42, v43
	v_cvt_pk_bf16_f32 v43, v50, v51
	s_mov_b64 s[0:1], 0x280000
	s_nop 0
	v_addc_co_u32_e32 v47, vcc, 0, v143, vcc
	global_store_dwordx4 v[46:47], v[40:43], off sc0 sc1
	s_nop 1
	v_pk_fma_f32 v[40:41], v[30:31], v[156:157], v[162:163] op_sel_hi:[1,1,0]
	v_pk_fma_f32 v[30:31], v[28:29], v[154:155], v[162:163] op_sel_hi:[1,1,0]
	v_cvt_pk_bf16_f32 v28, v36, v37
	v_cvt_pk_bf16_f32 v29, v38, v39
	s_nop 0
	v_cvt_pk_bf16_f32 v30, v30, v31
	v_cvt_pk_bf16_f32 v31, v40, v41
	global_store_dwordx4 v[44:45], v[28:31], off offset:256 sc0 sc1
	s_nop 1
	v_lshl_add_u64 v[28:29], v[142:143], 0, s[0:1]
	v_pk_fma_f32 v[30:31], v[34:35], v[140:141], v[160:161] op_sel_hi:[1,1,0]
	s_mov_b32 s0, 0x280000
	v_pk_fma_f32 v[34:35], v[26:27], v[148:149], v[160:161] op_sel_hi:[1,1,0]
	v_pk_fma_f32 v[26:27], v[24:25], v[144:145], v[160:161] op_sel_hi:[1,1,0]
	v_cvt_pk_bf16_f32 v25, v30, v31
	v_add_co_u32_e32 v30, vcc, s0, v142
	v_cvt_pk_bf16_f32 v24, v32, v33
	v_cvt_pk_bf16_f32 v26, v26, v27
	v_cvt_pk_bf16_f32 v27, v34, v35
	s_mov_b64 s[0:1], 0x2c0000
	s_nop 0
	v_addc_co_u32_e32 v31, vcc, 0, v143, vcc
	global_store_dwordx4 v[30:31], v[24:27], off sc0 sc1
	s_nop 1
	v_pk_fma_f32 v[24:25], v[14:15], v[156:157], v[160:161] op_sel_hi:[1,1,0]
	v_pk_fma_f32 v[14:15], v[12:13], v[154:155], v[160:161] op_sel_hi:[1,1,0]
	v_cvt_pk_bf16_f32 v12, v20, v21
	v_cvt_pk_bf16_f32 v13, v22, v23
	s_nop 0
	v_cvt_pk_bf16_f32 v14, v14, v15
	v_cvt_pk_bf16_f32 v15, v24, v25
	global_store_dwordx4 v[28:29], v[12:15], off offset:256 sc0 sc1
	s_nop 1
	v_lshl_add_u64 v[12:13], v[142:143], 0, s[0:1]
	v_pk_fma_f32 v[14:15], v[18:19], v[140:141], v[146:147] op_sel_hi:[1,1,0]
	s_mov_b32 s0, 0x2c0000
	v_pk_fma_f32 v[18:19], v[10:11], v[148:149], v[146:147] op_sel_hi:[1,1,0]
	v_pk_fma_f32 v[10:11], v[8:9], v[144:145], v[146:147] op_sel_hi:[1,1,0]
	v_cvt_pk_bf16_f32 v9, v14, v15
	v_add_co_u32_e32 v14, vcc, s0, v142
	v_cvt_pk_bf16_f32 v8, v16, v17
	v_cvt_pk_bf16_f32 v10, v10, v11
	v_cvt_pk_bf16_f32 v11, v18, v19
	s_mov_b64 s[0:1], -1
	s_nop 0
	v_addc_co_u32_e32 v15, vcc, 0, v143, vcc
	global_store_dwordx4 v[14:15], v[8:11], off sc0 sc1
	s_andn2_b64 vcc, exec, s[28:29]
	s_nop 0
	v_pk_fma_f32 v[8:9], v[2:3], v[156:157], v[146:147] op_sel_hi:[1,1,0]
	v_pk_fma_f32 v[2:3], v[0:1], v[154:155], v[146:147] op_sel_hi:[1,1,0]
	v_cvt_pk_bf16_f32 v0, v4, v5
	v_cvt_pk_bf16_f32 v1, v6, v7
	s_nop 0
	v_cvt_pk_bf16_f32 v2, v2, v3
	v_cvt_pk_bf16_f32 v3, v8, v9
	global_store_dwordx4 v[12:13], v[0:3], off offset:256 sc0 sc1
	s_cbranch_vccnz .LBB0_356
	s_andn2_b64 vcc, exec, s[8:9]
	s_cbranch_vccnz .LBB0_355
	s_barrier
	s_branch .LBB0_355
